# F2 fused GEMM visits its 4 row-panel rounds in reverse so the most recently written HID panels are read first (cache locality)
# speedup vs baseline: 1.0089x; 1.0089x over previous
.LBB0_455:
	s_cmp_gt_i32 s81, 1
	v_writelane_b32 v255, s4, 49
	s_cselect_b64 s[0:1], -1, 0
	s_cmp_lt_i32 s80, 2
	v_writelane_b32 v255, s5, 50
	s_cselect_b32 s4, 7, 5
	s_cmp_lt_i32 s81, s4
	v_writelane_b32 v255, s3, 51
	s_cselect_b64 s[2:3], -1, 0
	s_and_b64 s[6:7], s[2:3], exec
	s_cselect_b32 s5, 1, 2
	s_and_b64 s[0:1], s[0:1], s[2:3]
	s_and_b64 vcc, s[0:1], exec
	s_cselect_b32 s6, 3, 5
	s_cmp_gt_i32 s81, 1
	v_cndmask_b32_e64 v209, 0.5, 1.0, s[0:1]
	s_cselect_b64 s[0:1], -1, 0
	s_and_b64 s[2:3], s[0:1], exec
	s_cselect_b32 s5, s5, 0
	s_cselect_b32 s2, s6, 1
	s_add_u32 s46, s60, 0x100000
	s_addc_u32 s47, s61, 0
	s_add_u32 s44, s60, 0xa000000
	s_addc_u32 s45, s61, 0
	s_add_u32 s48, s60, 0x12000000
	s_addc_u32 s49, s61, 0
	s_cmp_gt_i32 s80, 1
	s_mul_i32 s3, s80, 6
	s_cselect_b64 s[12:13], -1, 0
	s_add_i32 s2, s2, s3
	s_lshl_b32 s2, s2, 10
	s_ashr_i32 s3, s2, 31
	s_lshl_b64 s[2:3], s[2:3], 2
	s_add_u32 s2, s60, s2
	s_addc_u32 s3, s61, s3
	s_add_u32 s68, s2, 0x3d000000
	s_addc_u32 s69, s3, 0
	s_cmp_eq_u32 s80, 3
	s_cselect_b64 s[2:3], -1, 0
	s_cmp_eq_u32 s5, 2
	s_cselect_b64 s[6:7], -1, 0
	s_and_b64 s[2:3], s[2:3], s[6:7]
	v_readlane_b32 s8, v254, 0
	s_and_b64 s[2:3], s[2:3], exec
	v_readlane_b32 s10, v254, 2
	v_readlane_b32 s11, v254, 3
	s_mov_b64 s[2:3], s[10:11]
	s_cselect_b32 s39, s3, 0
	s_cselect_b32 s38, s2, 0
	s_add_u32 s76, s60, 0x9e00000
	s_mul_i32 s2, s80, 3
	s_addc_u32 s77, s61, 0
	s_add_i32 s5, s5, s2
	s_lshl_b32 s2, s5, 5
	s_add_i32 s84, s2, 32
	s_mov_b64 s[2:3], -1
	v_readlane_b32 s9, v254, 1
	s_cbranch_vccnz .LBB0_582
	v_cndmask_b32_e64 v0, 0, 1, s[0:1]
	s_and_b64 s[0:1], s[0:1], exec
	s_cselect_b32 s0, s4, 0
	s_lshl_b32 s1, s80, 1
	v_readfirstlane_b32 s2, v0
	s_or_b32 s1, s1, s2
	s_mul_hi_i32 s2, s1, 0x1080000
	s_mul_i32 s1, s1, 0x1080000
	s_add_u32 s1, s60, s1
	s_addc_u32 s2, s61, s2
	s_add_u32 s30, s1, 0x200000
	s_addc_u32 s31, s2, 0
	s_cmp_lg_u32 s81, s0
	s_mov_b64 s[0:1], -1
	s_cbranch_scc0 .LBB0_560
	v_readlane_b32 s0, v254, 9
	s_waitcnt vmcnt(0)
	v_mov_b32_e32 v12, v200
	v_readlane_b32 s1, v254, 10
	s_andn2_b64 vcc, exec, s[0:1]
	v_readfirstlane_b32 s1, v12
	s_cbranch_vccnz .LBB0_559
	v_lshlrev_b32_e32 v0, 4, v12
	s_waitcnt lgkmcnt(0)
	v_add_u32_e32 v1, 0x2000, v0
	v_ashrrev_i32_e32 v2, 31, v1
	v_lshrrev_b32_e32 v2, 22, v2
	v_add_u32_e32 v2, v1, v2
	v_ashrrev_i32_e32 v8, 10, v2
	v_mul_i32_i24_e32 v2, 0x400, v8
	v_sub_u32_e32 v1, v1, v2
	v_lshrrev_b32_e32 v2, 4, v1
	v_bitop3_b32 v1, v2, v1, 32 bitop3:0x6c
	v_ashrrev_i32_e32 v2, 31, v1
	v_lshrrev_b32_e32 v2, 26, v2
	v_add_u32_e32 v2, v1, v2
	v_lshlrev_b32_e32 v3, 3, v8
	v_ashrrev_i32_e32 v9, 6, v2
	v_and_b32_e32 v3, -16, v3
	v_add_u32_e32 v3, v9, v3
	v_and_b32_e32 v4, 3, v9
	s_mov_b32 s3, 0xffffe0
	v_lshrrev_b32_e32 v5, 2, v3
	v_lshlrev_b32_e32 v6, 1, v3
	v_and_b32_e32 v2, 0xc0, v2
	v_and_or_b32 v4, v3, s3, v4
	v_and_b32_e32 v5, 4, v5
	v_and_b32_e32 v6, 24, v6
	v_sub_u32_e32 v1, v1, v2
	v_or3_b32 v4, v4, v5, v6
	v_lshlrev_b32_e32 v5, 5, v8
	v_ashrrev_i16_sdwa v1, v207, sext(v1) dst_sel:DWORD dst_unused:UNUSED_PAD src0_sel:DWORD src1_sel:BYTE_0
	v_and_b32_e32 v10, 32, v5
	v_bfe_i32 v11, v1, 0, 16
	s_movk_i32 s4, 0xb00
	v_mul_u32_u24_e32 v4, 0xb00, v4
	v_add_u32_e32 v1, v10, v11
	v_mul_lo_u32 v2, v3, s4
	v_add_lshl_u32 v182, v4, v1, 1
	v_add_lshl_u32 v184, v1, v2, 1
	v_bfe_i32 v1, v12, 27, 1
	v_lshrrev_b32_e32 v1, 22, v1
	v_add_u32_e32 v1, v0, v1
	v_and_b32_e32 v1, 0xfffffc00, v1
	v_sub_u32_e32 v0, v0, v1
	v_lshrrev_b32_e32 v1, 4, v0
	v_ashrrev_i32_e32 v2, 31, v12
	v_bitop3_b32 v0, v1, v0, 32 bitop3:0x6c
	v_lshrrev_b32_e32 v2, 26, v2
	v_ashrrev_i32_e32 v1, 31, v0
	v_add_u32_e32 v2, v12, v2
	v_lshrrev_b32_e32 v1, 26, v1
	s_waitcnt vmcnt(4)
	v_ashrrev_i32_e32 v14, 6, v2
	v_add_u32_e32 v1, v0, v1
	v_lshlrev_b32_e32 v2, 3, v14
	v_ashrrev_i32_e32 v13, 6, v1
	v_and_b32_e32 v2, -16, v2
	v_add_u32_e32 v2, v13, v2
	s_add_u32 s34, s30, 0xb00000
	v_and_b32_e32 v3, 3, v13
	v_lshrrev_b32_e32 v4, 2, v2
	v_lshlrev_b32_e32 v5, 1, v2
	v_and_b32_e32 v1, 0xc0, v1
	s_addc_u32 s35, s31, 0
	s_ashr_i32 s2, s1, 6
	v_and_or_b32 v3, v2, s3, v3
	v_and_b32_e32 v4, 4, v4
	v_and_b32_e32 v5, 24, v5
	v_sub_u32_e32 v0, v0, v1
	v_mul_lo_u32 v1, v2, s4
	v_readlane_b32 s4, v255, 5
	s_ashr_i32 s0, s1, 8
	s_lshl_b32 s36, s2, 10
	v_or3_b32 v3, v3, v4, v5
	v_lshlrev_b32_e32 v4, 5, v14
	v_ashrrev_i16_sdwa v0, v207, sext(v0) dst_sel:DWORD dst_unused:UNUSED_PAD src0_sel:DWORD src1_sel:BYTE_0
	s_mul_i32 s3, s4, 0x160000
	v_and_b32_e32 v15, 32, v4
	v_bfe_i32 v16, v0, 0, 16
	s_add_u32 s26, s34, s3
	s_mul_hi_i32 s3, s4, 0x160000
	v_mul_u32_u24_e32 v3, 0xb00, v3
	v_add_u32_e32 v0, v15, v16
	s_addc_u32 s27, s35, s3
	s_add_i32 s37, s36, 0
	v_add_lshl_u32 v176, v3, v0, 1
	s_add_i32 m0, s37, 0x10000
	v_add_lshl_u32 v186, v0, v1, 1
	global_load_lds_dwordx4 v176, s[26:27]
	s_add_i32 m0, s37, 0x12000
	s_add_u32 s4, s26, 0xb0000
	global_load_lds_dwordx4 v182, s[26:27]
	s_addc_u32 s5, s27, 0
	s_add_i32 m0, s37, 0x14000
	v_mov_b32_e32 v183, v177
	global_load_lds_dwordx4 v176, s[4:5]
	s_add_i32 m0, s37, 0x16000
	v_mov_b32_e32 v187, v177
	global_load_lds_dwordx4 v182, s[4:5]
	v_readlane_b32 s4, v255, 10
	s_cmpk_eq_i32 s58, 0x100
	s_cselect_b32 s3, 24, 0
	s_add_i32 s4, s4, s3
	s_mul_i32 s3, s4, 0x160000
	s_add_u32 s10, s48, s3
	s_mul_hi_i32 s3, s4, 0x160000
	s_addc_u32 s11, s49, s3
	s_add_i32 s42, s37, 0x2000
	v_readlane_b32 s5, v255, 11
	s_mov_b32 m0, s37
	s_add_u32 s4, s10, 0xb0000
	global_load_lds_dwordx4 v186, s[10:11]
	s_mov_b32 m0, s42
	s_addc_u32 s5, s11, 0
	s_add_i32 s43, s37, 0x4000
	global_load_lds_dwordx4 v184, s[10:11]
	s_mov_b32 m0, s43
	s_add_i32 s50, s37, 0x6000
	global_load_lds_dwordx4 v186, s[4:5]
	s_mov_b32 m0, s50
	v_mov_b32_e32 v185, v177
	global_load_lds_dwordx4 v184, s[4:5]
	s_cmp_eq_u32 s0, 1
	v_lshl_add_u64 v[6:7], s[26:27], 0, v[176:177]
	v_lshl_add_u64 v[4:5], s[26:27], 0, v[182:183]
	v_lshl_add_u64 v[0:1], s[10:11], 0, v[186:187]
	s_cselect_b64 s[14:15], -1, 0
	s_cmp_lg_u32 s0, 1
	v_lshl_add_u64 v[2:3], s[10:11], 0, v[184:185]
	s_cbranch_scc1 .LBB0_460
	s_barrier
.LBB0_460:
	s_waitcnt vmcnt(0)
	v_and_b32_e32 v18, 15, v12
	v_bfe_u32 v17, v12, 4, 2
	v_lshl_or_b32 v210, s0, 6, v18
	v_lshlrev_b32_e32 v20, 4, v17
	v_lshlrev_b32_e32 v21, 2, v210
	s_and_b32 s8, s2, 3
	v_lshl_or_b32 v20, v18, 6, v20
	s_lshl_b32 s2, s0, 13
	v_and_b32_e32 v22, 32, v21
	v_lshlrev_b32_e32 v23, 2, v12
	s_add_i32 m0, s37, 0x18000
	v_lshl_add_u64 v[6:7], v[6:7], 0, s[72:73]
	v_bitop3_b32 v22, v20, s2, v22 bitop3:0xde
	s_lshl_b32 s2, s8, 12
	v_and_b32_e32 v23, 32, v23
	s_waitcnt vmcnt(2)
	s_barrier
	global_load_lds_dwordx4 v[6:7], off
	v_lshl_add_u64 v[4:5], v[4:5], 0, s[72:73]
	s_add_i32 m0, s37, 0x1a000
	s_add_i32 s51, s37, 0x8000
	s_add_i32 s54, s37, 0xa000
	v_bitop3_b32 v211, v20, s2, v23 bitop3:0xde
	global_load_lds_dwordx4 v[4:5], off
	v_lshl_add_u64 v[0:1], v[0:1], 0, s[72:73]
	s_mov_b32 m0, s51
	s_add_u32 s2, s26, 0xb0080
	global_load_lds_dwordx4 v[0:1], off
	v_lshl_add_u64 v[0:1], v[2:3], 0, s[72:73]
	s_mov_b32 m0, s54
	s_addc_u32 s3, s27, 0
	global_load_lds_dwordx4 v[0:1], off
	s_add_i32 m0, s37, 0x1c000
	v_lshl_add_u64 v[0:1], s[2:3], 0, v[176:177]
	global_load_lds_dwordx4 v[0:1], off
	v_lshl_add_u64 v[0:1], s[2:3], 0, v[182:183]
	s_add_i32 m0, s37, 0x1e000
	s_cmpk_lt_u32 s1, 0x100
	global_load_lds_dwordx4 v[0:1], off
	s_cselect_b64 s[16:17], -1, 0
	s_lshl_b32 s1, s0, 2
	s_or_b32 s1, s1, s8
	v_and_b32_e32 v0, 63, v12
	v_and_b32_e32 v1, 31, v12
	v_lshl_or_b32 v213, s1, 5, v1
	v_lshl_or_b32 v214, s1, 6, v0
	s_movk_i32 s1, 0x100
	v_cmp_gt_i32_e64 s[6:7], s1, v214
	s_lshl_b32 s1, s8, 2
	s_add_i32 s1, s1, 0
	s_lshl_b32 s0, s0, 10
	s_add_i32 s9, s1, 0x20400
	s_add_i32 s20, s9, s0
	s_lshl_b32 s0, s8, 7
	v_readlane_b32 s1, v255, 37
	v_lshlrev_b32_e32 v19, 3, v17
	s_add_i32 s1, s1, s0
	s_add_i32 s0, s0, 0
	v_lshl_or_b32 v212, s8, 5, v19
	v_lshlrev_b32_e32 v0, 5, v17
	s_add_i32 s0, s0, 0x21c00
	s_movk_i32 s8, 0xb00
	v_add_u32_e32 v222, s1, v0
	v_add_u32_e32 v223, s0, v0
	v_lshrrev_b32_e32 v1, 1, v8
	v_mul_lo_u32 v0, v9, s8
	s_mov_b32 s21, 0xb000
	v_mad_u64_u32 v[0:1], s[0:1], v1, s21, v[0:1]
	v_or_b32_e32 v0, v0, v10
	v_add_lshl_u32 v0, v0, v11, 1
	v_mov_b32_e32 v1, v177
	s_mov_b64 s[22:23], 0xb0080
	v_lshl_add_u64 v[188:189], v[0:1], 0, s[22:23]
	v_lshrrev_b32_e32 v1, 1, v14
	v_mul_lo_u32 v0, v13, s8
	v_mad_u64_u32 v[0:1], s[0:1], v1, s21, v[0:1]
	s_waitcnt vmcnt(6)
	v_lshlrev_b32_e32 v2, 4, v18
	v_add_u32_e32 v215, 0x80, v210
	v_or_b32_e32 v216, 16, v210
	v_or_b32_e32 v217, 32, v210
	v_or_b32_e32 v218, 48, v210
	v_add_u32_e32 v219, 0x90, v210
	v_add_u32_e32 v220, 0xa0, v210
	v_add_u32_e32 v221, 0xb0, v210
	v_or_b32_e32 v0, v0, v15
	v_readlane_b32 s0, v255, 5
	v_lshlrev_b32_e32 v3, 4, v213
	v_lshlrev_b32_e32 v4, 4, v210
	v_lshlrev_b32_e32 v5, 4, v216
	v_lshlrev_b32_e32 v6, 4, v217
	v_lshlrev_b32_e32 v7, 4, v218
	v_lshlrev_b32_e32 v12, 4, v215
	v_lshlrev_b32_e32 v18, 4, v219
	v_lshlrev_b32_e32 v19, 4, v220
	v_lshlrev_b32_e32 v20, 4, v221
	s_cmp_lg_u64 s[38:39], 0
	v_add_lshl_u32 v0, v0, v16, 1
	v_mov_b32_e32 v1, v177
	v_add_u32_e32 v234, s20, v2
	s_mov_b32 s20, s0
	v_readlane_b32 s0, v255, 10
	s_mov_b32 s55, 0
	v_cmp_eq_u32_e64 s[2:3], 0, v17
	v_cmp_gt_u32_e64 s[4:5], 2, v17
	v_add_u32_e32 v224, s63, v21
	s_cselect_b64 s[18:19], -1, 0
	v_lshl_add_u64 v[190:191], v[0:1], 0, s[22:23]
	s_mov_b32 s56, -1
	v_add_u32_e32 v225, 0, v22
	v_add_u32_e32 v226, s9, v4
	v_add_u32_e32 v227, s9, v5
	v_add_u32_e32 v228, s9, v6
	v_add_u32_e32 v229, s9, v7
	v_add_u32_e32 v230, s9, v12
	v_add_u32_e32 v231, s9, v18
	v_add_u32_e32 v232, s9, v19
	v_add_u32_e32 v233, s9, v20
	v_add_u32_e32 v235, 0, v3
	s_cmpk_eq_i32 s58, 0x100
	s_cselect_b32 s21, 24, 0
	s_add_i32 s21, s21, s0
	s_barrier
	v_readlane_b32 s1, v255, 11
	s_branch .LBB0_463

.LBB0_469:
	s_cmpk_lg_i32 s58, 0x100
	s_cbranch_scc1 .Lrev_skip0
	v_readlane_b32 s8, v255, 10
	s_lshl_b32 s9, s55, 3
	s_sub_i32 s8, s8, s9
	s_add_i32 s70, s8, 24
